# phase-1 GEMM K-loop stages tiles with global_load_lds (LDS-DMA) instead of VGPR staging + ds_write; same LDS image and epilogue
# speedup vs baseline: 1.0482x; 1.0482x over previous
.LBB0_112:
	v_writelane_b32 v237, s48, 51
	v_writelane_b32 v237, s44, 52
	s_nop 1
	v_writelane_b32 v237, s45, 53
	s_or_b64 exec, exec, s[0:1]
	s_add_u32 s74, s54, 0x2200000
	s_addc_u32 s75, s55, 0
	s_and_b32 s0, s72, 7
	s_cmp_lg_u32 s0, 0
	s_cselect_b64 s[50:51], -1, 0
	s_ashr_i32 s2, s96, 3
	s_ashr_i32 s3, s72, 3
	s_and_b32 s1, s96, 7
	s_cmp_eq_u32 s0, 0
	s_cselect_b64 s[4:5], -1, 0
	v_writelane_b32 v237, s1, 54
	s_mul_i32 s19, s1, 17
	v_writelane_b32 v237, s4, 55
	s_and_b64 s[0:1], s[4:5], exec
	s_movk_i32 s0, 0x1dc
	v_writelane_b32 v237, s5, 56
	s_cselect_b32 s49, s2, s96
	s_cselect_b32 s12, s0, 0xee0
	v_writelane_b32 v237, s3, 57
	s_cselect_b32 s48, s3, s72
	s_cmp_ge_i32 s49, s12
	v_and_b32_e32 v174, 15, v0
	s_barrier
	v_writelane_b32 v237, s2, 58
	s_cbranch_scc1 .LBB0_130
	v_lshrrev_b32_e32 v8, 3, v0
	v_lshlrev_b32_e32 v2, 11, v8
	v_mov_b32_e32 v3, 0
	v_lshl_add_u64 v[4:5], s[54:55], 0, v[2:3]
	v_lshlrev_b32_e32 v2, 4, v0
	v_and_b32_e32 v2, 0x70, v2
	v_lshl_add_u64 v[98:99], v[4:5], 0, v[2:3]
	v_xor_b32_e32 v4, v8, v0
	s_movk_i32 s4, 0x70
	v_lshlrev_b32_e32 v2, 7, v8
	v_lshlrev_b32_e32 v4, 4, v4
	v_lshrrev_b32_e32 v6, 4, v0
	v_and_or_b32 v108, v4, s4, v2
	v_and_b32_e32 v4, 7, v0
	v_bitop3_b32 v5, v6, v4, 3 bitop3:0x6c
	v_bfe_u32 v7, v0, 4, 2
	v_lshlrev_b32_e32 v109, 4, v5
	v_lshlrev_b32_e32 v5, 7, v0
	v_and_b32_e32 v112, 0x2780, v5
	v_bitop3_b32 v5, v7, v4, 4 bitop3:0x36
	s_mov_b64 s[2:3], 0xe680000
	v_lshrrev_b32_e32 v2, 1, v0
	v_lshlrev_b32_e32 v113, 4, v5
	v_and_b32_e32 v5, 64, v0
	v_lshl_add_u64 v[100:101], v[98:99], 0, s[2:3]
	v_and_or_b32 v110, v2, 64, v174
	v_and_or_b32 v114, v2, 24, v5
	v_lshlrev_b32_e32 v2, 8, v0
	v_lshlrev_b32_e32 v4, 4, v4
	s_mov_b32 s2, 0xf800
	s_add_u32 s0, s54, 0xf280000
	v_and_or_b32 v2, v2, s2, v4
	s_addc_u32 s1, s55, 0
	s_add_i32 s13, s19, 9
	v_lshlrev_b32_e32 v111, 7, v110
	v_lshl_add_u64 v[102:103], s[54:55], 0, v[2:3]
	s_mov_b32 s14, 0x10000
	s_mov_b32 s15, 0x20000
	s_mov_b32 s16, 0x30000
	s_movk_i32 s17, 0x1c00
	s_mov_b32 s18, s49
	v_lshrrev_b32_e32 v104, 3, v0
	v_lshlrev_b32_e32 v104, 11, v104
	v_and_b32_e32 v105, 0x70, v108
	v_or_b32_e32 v104, v104, v105
	v_add_u32_e32 v105, 0x10000, v104
	v_add_u32_e32 v106, 0x20000, v104
	v_add_u32_e32 v107, 0x30000, v104
	v_lshrrev_b32_e32 v115, 6, v0
	s_nop 1
	v_readfirstlane_b32 s30, v115
	s_nop 3
	s_lshl_b32 s30, s30, 10
	s_branch .LBB0_115

.LBB0_122:
	s_lshl_b32 s4, s4, 7
	s_lshl_b32 s2, s5, 7
	s_lshl_b32 s24, s4, 11
	s_add_u32 s26, s54, s24
	s_addc_u32 s27, s55, 0
	s_lshl_b32 s24, s2, 11
	s_add_u32 s28, s54, s24
	s_addc_u32 s29, s55, 0
	s_add_u32 s28, s28, 0xe680000
	s_addc_u32 s29, s29, 0
	s_barrier
	s_mov_b32 m0, s30
	s_nop 0
	global_load_lds_dwordx4 v104, s[26:27]
	s_add_u32 m0, s30, 0x1000
	s_nop 0
	global_load_lds_dwordx4 v105, s[26:27]
	s_add_u32 m0, s30, 0x2000
	s_nop 0
	global_load_lds_dwordx4 v106, s[26:27]
	s_add_u32 m0, s30, 0x3000
	s_nop 0
	global_load_lds_dwordx4 v107, s[26:27]
	s_add_u32 m0, s30, 0x4000
	s_nop 0
	global_load_lds_dwordx4 v104, s[28:29]
	s_add_u32 m0, s30, 0x5000
	s_nop 0
	global_load_lds_dwordx4 v105, s[28:29]
	s_add_u32 m0, s30, 0x6000
	s_nop 0
	global_load_lds_dwordx4 v106, s[28:29]
	s_add_u32 m0, s30, 0x7000
	s_nop 0
	global_load_lds_dwordx4 v107, s[28:29]
	v_mov_b32_e32 v2, 0
	v_mov_b32_e32 v3, v2
	v_mov_b32_e32 v4, v2
	v_mov_b32_e32 v5, v2
	v_mov_b32_e32 v6, v2
	v_mov_b32_e32 v7, v2
	v_mov_b32_e32 v8, v2
	v_mov_b32_e32 v9, v2
	v_mov_b32_e32 v10, v2
	v_mov_b32_e32 v11, v2
	v_mov_b32_e32 v12, v2
	v_mov_b32_e32 v13, v2
	v_mov_b32_e32 v14, v2
	v_mov_b32_e32 v15, v2
	v_mov_b32_e32 v16, v2
	v_mov_b32_e32 v17, v2
	v_mov_b32_e32 v18, v2
	v_mov_b32_e32 v19, v2
	v_mov_b32_e32 v20, v2
	v_mov_b32_e32 v21, v2
	v_mov_b32_e32 v22, v2
	v_mov_b32_e32 v23, v2
	v_mov_b32_e32 v24, v2
	v_mov_b32_e32 v25, v2
	v_mov_b32_e32 v26, v2
	v_mov_b32_e32 v27, v2
	v_mov_b32_e32 v28, v2
	v_mov_b32_e32 v29, v2
	v_mov_b32_e32 v30, v2
	v_mov_b32_e32 v31, v2
	v_mov_b32_e32 v32, v2
	v_mov_b32_e32 v33, v2
	v_mov_b32_e32 v34, v2
	v_mov_b32_e32 v35, v2
	v_mov_b32_e32 v36, v2
	v_mov_b32_e32 v37, v2
	v_mov_b32_e32 v46, v2
	v_mov_b32_e32 v47, v2
	v_mov_b32_e32 v48, v2
	v_mov_b32_e32 v49, v2
	v_mov_b32_e32 v50, v2
	v_mov_b32_e32 v51, v2
	v_mov_b32_e32 v52, v2
	v_mov_b32_e32 v53, v2
	v_mov_b32_e32 v58, v2
	v_mov_b32_e32 v59, v2
	v_mov_b32_e32 v60, v2
	v_mov_b32_e32 v61, v2
	v_mov_b32_e32 v82, v2
	v_mov_b32_e32 v83, v2
	v_mov_b32_e32 v84, v2
	v_mov_b32_e32 v85, v2
	v_mov_b32_e32 v86, v2
	v_mov_b32_e32 v87, v2
	v_mov_b32_e32 v88, v2
	v_mov_b32_e32 v89, v2
	v_mov_b32_e32 v90, v2
	v_mov_b32_e32 v91, v2
	v_mov_b32_e32 v92, v2
	v_mov_b32_e32 v93, v2
	v_mov_b32_e32 v94, v2
	v_mov_b32_e32 v95, v2
	v_mov_b32_e32 v96, v2
	v_mov_b32_e32 v97, v2
	s_mov_b32 s3, 0
	s_mov_b32 s10, 0
	s_waitcnt vmcnt(0)
	s_barrier
.Lg1_loop:
	v_or_b32_e32 v115, s10, v109
	v_add_u32_e32 v136, v115, v112
	ds_read_b128 v[116:119], v136 offset:16384
	v_add_u32_e32 v115, v115, v111
	ds_read_b128 v[120:123], v136 offset:18432
	ds_read_b128 v[124:127], v115
	ds_read_b128 v[128:131], v115 offset:2048
	ds_read_b128 v[132:135], v136 offset:20480
	ds_read_b128 v[136:139], v136 offset:22528
	s_cmp_eq_u32 s3, 15
	s_cbranch_scc1 .Lg1_noload
	s_add_u32 s26, s26, 0x80
	s_addc_u32 s27, s27, 0
	s_add_u32 s28, s28, 0x80
	s_addc_u32 s29, s29, 0
	s_xor_b32 s31, s10, 0x8000
	s_add_u32 s31, s31, s30
	s_mov_b32 m0, s31
	s_nop 0
	global_load_lds_dwordx4 v104, s[26:27]
	s_add_u32 m0, s31, 0x1000
	s_nop 0
	global_load_lds_dwordx4 v105, s[26:27]
	s_add_u32 m0, s31, 0x2000
	s_nop 0
	global_load_lds_dwordx4 v106, s[26:27]
	s_add_u32 m0, s31, 0x3000
	s_nop 0
	global_load_lds_dwordx4 v107, s[26:27]
	s_add_u32 m0, s31, 0x4000
	s_nop 0
	global_load_lds_dwordx4 v104, s[28:29]
	s_add_u32 m0, s31, 0x5000
	s_nop 0
	global_load_lds_dwordx4 v105, s[28:29]
	s_add_u32 m0, s31, 0x6000
	s_nop 0
	global_load_lds_dwordx4 v106, s[28:29]
	s_add_u32 m0, s31, 0x7000
	s_nop 0
	global_load_lds_dwordx4 v107, s[28:29]
.Lg1_noload:
	s_waitcnt lgkmcnt(3)
	v_mfma_f32_16x16x32_bf16 v[90:93], v[120:123], v[124:127], v[90:93]
	v_mfma_f32_16x16x32_bf16 v[94:97], v[116:119], v[124:127], v[94:97]
	s_waitcnt lgkmcnt(1)
	v_mfma_f32_16x16x32_bf16 v[86:89], v[132:135], v[124:127], v[86:89]
	s_waitcnt lgkmcnt(0)
	v_mfma_f32_16x16x32_bf16 v[82:85], v[136:139], v[124:127], v[82:85]
	v_mfma_f32_16x16x32_bf16 v[58:61], v[116:119], v[128:131], v[58:61]
	v_mfma_f32_16x16x32_bf16 v[50:53], v[120:123], v[128:131], v[50:53]
	v_mfma_f32_16x16x32_bf16 v[46:49], v[132:135], v[128:131], v[46:49]
	v_mfma_f32_16x16x32_bf16 v[34:37], v[136:139], v[128:131], v[34:37]
	ds_read_b128 v[124:127], v115 offset:4096
	ds_read_b128 v[128:131], v115 offset:6144
	v_or_b32_e32 v115, s10, v113
	v_add_u32_e32 v140, v115, v112
	s_waitcnt lgkmcnt(1)
	v_mfma_f32_16x16x32_bf16 v[30:33], v[116:119], v[124:127], v[30:33]
	v_add_u32_e32 v115, v115, v111
	v_mfma_f32_16x16x32_bf16 v[26:29], v[120:123], v[124:127], v[26:29]
	v_mfma_f32_16x16x32_bf16 v[22:25], v[132:135], v[124:127], v[22:25]
	v_mfma_f32_16x16x32_bf16 v[18:21], v[136:139], v[124:127], v[18:21]
	s_waitcnt lgkmcnt(0)
	v_mfma_f32_16x16x32_bf16 v[14:17], v[116:119], v[128:131], v[14:17]
	ds_read_b128 v[116:119], v140 offset:16384
	v_mfma_f32_16x16x32_bf16 v[10:13], v[120:123], v[128:131], v[10:13]
	v_mfma_f32_16x16x32_bf16 v[6:9], v[132:135], v[128:131], v[6:9]
	v_mfma_f32_16x16x32_bf16 v[2:5], v[136:139], v[128:131], v[2:5]
	ds_read_b128 v[120:123], v140 offset:18432
	ds_read_b128 v[124:127], v115
	ds_read_b128 v[128:131], v115 offset:2048
	ds_read_b128 v[132:135], v140 offset:20480
	ds_read_b128 v[136:139], v140 offset:22528
	s_waitcnt lgkmcnt(3)
	v_mfma_f32_16x16x32_bf16 v[94:97], v[116:119], v[124:127], v[94:97]
	v_mfma_f32_16x16x32_bf16 v[90:93], v[120:123], v[124:127], v[90:93]
	s_waitcnt lgkmcnt(1)
	v_mfma_f32_16x16x32_bf16 v[86:89], v[132:135], v[124:127], v[86:89]
	s_waitcnt lgkmcnt(0)
	v_mfma_f32_16x16x32_bf16 v[82:85], v[136:139], v[124:127], v[82:85]
	v_mfma_f32_16x16x32_bf16 v[58:61], v[116:119], v[128:131], v[58:61]
	v_mfma_f32_16x16x32_bf16 v[50:53], v[120:123], v[128:131], v[50:53]
	v_mfma_f32_16x16x32_bf16 v[46:49], v[132:135], v[128:131], v[46:49]
	v_mfma_f32_16x16x32_bf16 v[34:37], v[136:139], v[128:131], v[34:37]
	ds_read_b128 v[124:127], v115 offset:4096
	ds_read_b128 v[128:131], v115 offset:6144
	s_waitcnt lgkmcnt(1)
	v_mfma_f32_16x16x32_bf16 v[30:33], v[116:119], v[124:127], v[30:33]
	v_mfma_f32_16x16x32_bf16 v[26:29], v[120:123], v[124:127], v[26:29]
	v_mfma_f32_16x16x32_bf16 v[22:25], v[132:135], v[124:127], v[22:25]
	v_mfma_f32_16x16x32_bf16 v[18:21], v[136:139], v[124:127], v[18:21]
	s_waitcnt lgkmcnt(0)
	v_mfma_f32_16x16x32_bf16 v[14:17], v[116:119], v[128:131], v[14:17]
	v_mfma_f32_16x16x32_bf16 v[10:13], v[120:123], v[128:131], v[10:13]
	v_mfma_f32_16x16x32_bf16 v[6:9], v[132:135], v[128:131], v[6:9]
	v_mfma_f32_16x16x32_bf16 v[2:5], v[136:139], v[128:131], v[2:5]
	s_add_i32 s3, s3, 1
	s_xor_b32 s10, s10, 0x8000
	s_waitcnt vmcnt(0) lgkmcnt(0)
	s_barrier
	s_cmp_lg_u32 s3, 16
	s_cbranch_scc1 .Lg1_loop
	s_branch .LBB0_114
